# loop-head alignment: .p2align 6 before the four GEMM K-loop heads and the attention item loop (instruction-fetch placement)
# baseline (speedup 1.0000x reference)
.Lpk0_LBB0_63:
.Lpk0_LBB0_64:
	s_add_u32 s4, s0, 0x100
	s_addc_u32 s5, s1, 0
	s_and_b64 s[56:57], s[6:7], exec
	s_cselect_b32 s8, 0, s4
	s_add_u32 s55, s31, s0
	s_addc_u32 s56, s53, s1
	s_and_b64 s[0:1], s[6:7], exec
	s_cselect_b32 s1, s21, s56
	s_cselect_b32 s0, s27, s55
	s_add_u32 s98, s2, s8
	s_addc_u32 s99, s3, s9
	s_mov_b32 m0, s35
	s_add_u32 s6, s0, 0x40000
	ds_read_b128 v[190:193], v180 offset:16384
	ds_read_b128 v[194:197], v180 offset:17408
	ds_read_b128 v[198:201], v180 offset:18432
	ds_read_b128 v[202:205], v180 offset:19456
	ds_read_b128 v[206:209], v180 offset:20480
	ds_read_b128 v[210:213], v180 offset:21504
	ds_read_b128 v[214:217], v180 offset:22528
	ds_read_b128 v[218:221], v180 offset:23552
	global_load_lds_dwordx4 v160, s[0:1]
	s_mov_b32 m0, s36
	s_addc_u32 s7, s1, 0
	global_load_lds_dwordx4 v162, s[0:1]
	s_mov_b32 m0, s37
	s_nop 0
	global_load_lds_dwordx4 v160, s[6:7]
	s_mov_b32 m0, s38
	s_nop 0
	global_load_lds_dwordx4 v162, s[6:7]
	s_waitcnt vmcnt(6)
	s_waitcnt lgkmcnt(0)
	s_barrier
	s_setprio 1
	s_waitcnt lgkmcnt(0)
	v_mfma_f32_16x16x32_bf16 v[60:63], v[144:147], v[190:193], 0
	v_mfma_f32_16x16x32_bf16 v[56:59], v[152:155], v[190:193], 0
	v_mfma_f32_16x16x32_bf16 v[44:47], v[144:147], v[198:201], 0
	v_mfma_f32_16x16x32_bf16 v[40:43], v[152:155], v[198:201], 0
	v_mfma_f32_16x16x32_bf16 v[28:31], v[144:147], v[206:209], 0
	v_mfma_f32_16x16x32_bf16 v[24:27], v[152:155], v[206:209], 0
	v_mfma_f32_16x16x32_bf16 v[12:15], v[144:147], v[214:217], 0
	v_mfma_f32_16x16x32_bf16 v[8:11], v[152:155], v[214:217], 0
	v_mfma_f32_16x16x32_bf16 v[60:63], v[148:151], v[194:197], v[60:63]
	v_mfma_f32_16x16x32_bf16 v[56:59], v[156:159], v[194:197], v[56:59]
	v_mfma_f32_16x16x32_bf16 v[44:47], v[148:151], v[202:205], v[44:47]
	v_mfma_f32_16x16x32_bf16 v[40:43], v[156:159], v[202:205], v[40:43]
	v_mfma_f32_16x16x32_bf16 v[28:31], v[148:151], v[210:213], v[28:31]
	v_mfma_f32_16x16x32_bf16 v[24:27], v[156:159], v[210:213], v[24:27]
	v_mfma_f32_16x16x32_bf16 v[12:15], v[148:151], v[218:221], v[12:15]
	v_mfma_f32_16x16x32_bf16 v[8:11], v[156:159], v[218:221], v[8:11]
	v_mfma_f32_16x16x32_bf16 v[52:55], v[128:131], v[190:193], 0
	v_mfma_f32_16x16x32_bf16 v[48:51], v[136:139], v[190:193], 0
	v_mfma_f32_16x16x32_bf16 v[36:39], v[128:131], v[198:201], 0
	v_mfma_f32_16x16x32_bf16 v[32:35], v[136:139], v[198:201], 0
	v_mfma_f32_16x16x32_bf16 v[20:23], v[128:131], v[206:209], 0
	v_mfma_f32_16x16x32_bf16 v[16:19], v[136:139], v[206:209], 0
	v_mfma_f32_16x16x32_bf16 v[4:7], v[128:131], v[214:217], 0
	v_mfma_f32_16x16x32_bf16 v[0:3], v[136:139], v[214:217], 0
	v_mfma_f32_16x16x32_bf16 v[52:55], v[132:135], v[194:197], v[52:55]
	v_mfma_f32_16x16x32_bf16 v[48:51], v[140:143], v[194:197], v[48:51]
	v_mfma_f32_16x16x32_bf16 v[36:39], v[132:135], v[202:205], v[36:39]
	v_mfma_f32_16x16x32_bf16 v[32:35], v[140:143], v[202:205], v[32:35]
	v_mfma_f32_16x16x32_bf16 v[20:23], v[132:135], v[210:213], v[20:23]
	v_mfma_f32_16x16x32_bf16 v[16:19], v[140:143], v[210:213], v[16:19]
	v_mfma_f32_16x16x32_bf16 v[4:7], v[132:135], v[218:221], v[4:7]
	v_mfma_f32_16x16x32_bf16 v[0:3], v[140:143], v[218:221], v[0:3]
	s_setprio 0
	s_barrier
	s_add_i32 s6, 0, 0x18000
	s_add_i32 s7, 0, 0x1c000
	v_add_u32_e32 v140, s6, v176
	v_add_u32_e32 v156, s7, v176
	ds_read_b128 v[128:131], v140
	ds_read_b128 v[132:135], v140 offset:1024
	ds_read_b128 v[136:139], v140 offset:2048
	ds_read_b128 v[140:143], v140 offset:3072
	ds_read_b128 v[144:147], v156
	ds_read_b128 v[148:151], v156 offset:1024
	ds_read_b128 v[152:155], v156 offset:2048
	ds_read_b128 v[156:159], v156 offset:3072
	s_mov_b32 m0, s40
	ds_read_b128 v[190:193], v180 offset:32768
	ds_read_b128 v[194:197], v180 offset:33792
	ds_read_b128 v[198:201], v180 offset:34816
	ds_read_b128 v[202:205], v180 offset:35840
	ds_read_b128 v[206:209], v180 offset:36864
	ds_read_b128 v[210:213], v180 offset:37888
	ds_read_b128 v[214:217], v180 offset:38912
	ds_read_b128 v[218:221], v180 offset:39936
	global_load_lds_dwordx4 v168, s[98:99]
	s_mov_b32 m0, s41
	s_nop 0
	global_load_lds_dwordx4 v170, s[98:99]
	s_mov_b32 m0, s34
	s_nop 0
	global_load_lds_dwordx4 v164, s[98:99]
	s_mov_b32 m0, s39
	s_nop 0
	global_load_lds_dwordx4 v166, s[98:99]
	s_waitcnt vmcnt(8)
	s_waitcnt lgkmcnt(0)
	s_barrier
	s_setprio 1
	s_waitcnt lgkmcnt(0)
	v_mfma_f32_16x16x32_bf16 v[124:127], v[128:131], v[190:193], v[124:127]
	v_mfma_f32_16x16x32_bf16 v[120:123], v[136:139], v[190:193], v[120:123]
	v_mfma_f32_16x16x32_bf16 v[108:111], v[128:131], v[198:201], v[108:111]
	v_mfma_f32_16x16x32_bf16 v[104:107], v[136:139], v[198:201], v[104:107]
	v_mfma_f32_16x16x32_bf16 v[92:95], v[128:131], v[206:209], v[92:95]
	v_mfma_f32_16x16x32_bf16 v[88:91], v[136:139], v[206:209], v[88:91]
	v_mfma_f32_16x16x32_bf16 v[76:79], v[128:131], v[214:217], v[76:79]
	v_mfma_f32_16x16x32_bf16 v[72:75], v[136:139], v[214:217], v[72:75]
	v_mfma_f32_16x16x32_bf16 v[124:127], v[132:135], v[194:197], v[124:127]
	v_mfma_f32_16x16x32_bf16 v[120:123], v[140:143], v[194:197], v[120:123]
	v_mfma_f32_16x16x32_bf16 v[108:111], v[132:135], v[202:205], v[108:111]
	v_mfma_f32_16x16x32_bf16 v[104:107], v[140:143], v[202:205], v[104:107]
	v_mfma_f32_16x16x32_bf16 v[92:95], v[132:135], v[210:213], v[92:95]
	v_mfma_f32_16x16x32_bf16 v[88:91], v[140:143], v[210:213], v[88:91]
	v_mfma_f32_16x16x32_bf16 v[76:79], v[132:135], v[218:221], v[76:79]
	v_mfma_f32_16x16x32_bf16 v[72:75], v[140:143], v[218:221], v[72:75]
	v_mfma_f32_16x16x32_bf16 v[116:119], v[144:147], v[190:193], v[116:119]
	v_mfma_f32_16x16x32_bf16 v[112:115], v[152:155], v[190:193], v[112:115]
	v_mfma_f32_16x16x32_bf16 v[100:103], v[144:147], v[198:201], v[100:103]
	v_mfma_f32_16x16x32_bf16 v[96:99], v[152:155], v[198:201], v[96:99]
	v_mfma_f32_16x16x32_bf16 v[84:87], v[144:147], v[206:209], v[84:87]
	v_mfma_f32_16x16x32_bf16 v[80:83], v[152:155], v[206:209], v[80:83]
	v_mfma_f32_16x16x32_bf16 v[68:71], v[144:147], v[214:217], v[68:71]
	v_mfma_f32_16x16x32_bf16 v[64:67], v[152:155], v[214:217], v[64:67]
	v_mfma_f32_16x16x32_bf16 v[116:119], v[148:151], v[194:197], v[116:119]
	v_mfma_f32_16x16x32_bf16 v[112:115], v[156:159], v[194:197], v[112:115]
	v_mfma_f32_16x16x32_bf16 v[100:103], v[148:151], v[202:205], v[100:103]
	v_mfma_f32_16x16x32_bf16 v[96:99], v[156:159], v[202:205], v[96:99]
	v_mfma_f32_16x16x32_bf16 v[84:87], v[148:151], v[210:213], v[84:87]
	v_mfma_f32_16x16x32_bf16 v[80:83], v[156:159], v[210:213], v[80:83]
	v_mfma_f32_16x16x32_bf16 v[68:71], v[148:151], v[218:221], v[68:71]
	v_mfma_f32_16x16x32_bf16 v[64:67], v[156:159], v[218:221], v[64:67]
	s_setprio 0
	s_barrier
	s_add_i32 s6, s6, s84
	s_add_u32 s100, s0, s14
	s_addc_u32 s101, s1, s15
	s_add_u32 s98, s98, s14
	s_addc_u32 s99, s99, s15
	s_mov_b32 m0, s6
	ds_read_b128 v[190:193], v180 offset:49152
	ds_read_b128 v[194:197], v180 offset:50176
	ds_read_b128 v[198:201], v180 offset:51200
	ds_read_b128 v[202:205], v180 offset:52224
	ds_read_b128 v[206:209], v180 offset:53248
	ds_read_b128 v[210:213], v180 offset:54272
	ds_read_b128 v[214:217], v180 offset:55296
	ds_read_b128 v[218:221], v180 offset:56320
	global_load_lds_dwordx4 v160, s[100:101]
	s_add_i32 m0, s6, 0x2000
	s_add_u32 s0, s0, 0x40080
	s_addc_u32 s1, s1, 0
	s_add_i32 s6, s7, s84
	global_load_lds_dwordx4 v162, s[100:101]
	s_mov_b32 m0, s6
	s_nop 0
	global_load_lds_dwordx4 v160, s[0:1]
	s_add_i32 m0, s6, 0x2000
	s_nop 0
	global_load_lds_dwordx4 v162, s[0:1]
	s_mov_b32 m0, s42
	s_nop 0
	global_load_lds_dwordx4 v164, s[98:99]
	s_mov_b32 m0, s43
	s_nop 0
	global_load_lds_dwordx4 v166, s[98:99]
	s_waitcnt vmcnt(6)
	s_waitcnt lgkmcnt(0)
	s_barrier
	s_setprio 1
	s_waitcnt lgkmcnt(0)
	v_mfma_f32_16x16x32_bf16 v[60:63], v[128:131], v[190:193], v[60:63]
	v_mfma_f32_16x16x32_bf16 v[56:59], v[136:139], v[190:193], v[56:59]
	v_mfma_f32_16x16x32_bf16 v[44:47], v[128:131], v[198:201], v[44:47]
	v_mfma_f32_16x16x32_bf16 v[40:43], v[136:139], v[198:201], v[40:43]
	v_mfma_f32_16x16x32_bf16 v[28:31], v[128:131], v[206:209], v[28:31]
	v_mfma_f32_16x16x32_bf16 v[24:27], v[136:139], v[206:209], v[24:27]
	v_mfma_f32_16x16x32_bf16 v[12:15], v[128:131], v[214:217], v[12:15]
	v_mfma_f32_16x16x32_bf16 v[8:11], v[136:139], v[214:217], v[8:11]
	v_mfma_f32_16x16x32_bf16 v[60:63], v[132:135], v[194:197], v[60:63]
	v_mfma_f32_16x16x32_bf16 v[56:59], v[140:143], v[194:197], v[56:59]
	v_mfma_f32_16x16x32_bf16 v[44:47], v[132:135], v[202:205], v[44:47]
	v_mfma_f32_16x16x32_bf16 v[40:43], v[140:143], v[202:205], v[40:43]
	v_mfma_f32_16x16x32_bf16 v[28:31], v[132:135], v[210:213], v[28:31]
	v_mfma_f32_16x16x32_bf16 v[24:27], v[140:143], v[210:213], v[24:27]
	v_mfma_f32_16x16x32_bf16 v[12:15], v[132:135], v[218:221], v[12:15]
	v_mfma_f32_16x16x32_bf16 v[8:11], v[140:143], v[218:221], v[8:11]
	v_mfma_f32_16x16x32_bf16 v[52:55], v[144:147], v[190:193], v[52:55]
	v_mfma_f32_16x16x32_bf16 v[48:51], v[152:155], v[190:193], v[48:51]
	v_mfma_f32_16x16x32_bf16 v[36:39], v[144:147], v[198:201], v[36:39]
	v_mfma_f32_16x16x32_bf16 v[32:35], v[152:155], v[198:201], v[32:35]
	v_mfma_f32_16x16x32_bf16 v[20:23], v[144:147], v[206:209], v[20:23]
	v_mfma_f32_16x16x32_bf16 v[16:19], v[152:155], v[206:209], v[16:19]
	v_mfma_f32_16x16x32_bf16 v[4:7], v[144:147], v[214:217], v[4:7]
	v_mfma_f32_16x16x32_bf16 v[0:3], v[152:155], v[214:217], v[0:3]
	v_mfma_f32_16x16x32_bf16 v[52:55], v[148:151], v[194:197], v[52:55]
	v_mfma_f32_16x16x32_bf16 v[48:51], v[156:159], v[194:197], v[48:51]
	v_mfma_f32_16x16x32_bf16 v[36:39], v[148:151], v[202:205], v[36:39]
	v_mfma_f32_16x16x32_bf16 v[32:35], v[156:159], v[202:205], v[32:35]
	v_mfma_f32_16x16x32_bf16 v[20:23], v[148:151], v[210:213], v[20:23]
	v_mfma_f32_16x16x32_bf16 v[16:19], v[156:159], v[210:213], v[16:19]
	v_mfma_f32_16x16x32_bf16 v[4:7], v[148:151], v[218:221], v[4:7]
	v_mfma_f32_16x16x32_bf16 v[0:3], v[156:159], v[218:221], v[0:3]
	s_setprio 0
	s_barrier
	s_add_i32 s54, s54, 2
	s_cmp_gt_u32 s54, 13
	s_cbranch_scc1 .LBB0_66
	s_mov_b64 s[0:1], s[4:5]
	s_branch .LBB0_61
	.p2align 6

.LBB0_244:
	s_cmpk_gt_i32 s71, 0x2fff
	v_writelane_b32 v253, s72, 43
	s_cbranch_scc1 .LBB0_248
	s_waitcnt vmcnt(10)
	v_ashrrev_i32_e32 v5, 4, v0
	v_bfe_u32 v1, v0, 2, 2
	v_lshlrev_b32_e32 v154, 2, v5
	s_mul_i32 s0, s72, 0x2400
	v_lshlrev_b32_e32 v6, 3, v0
	v_or_b32_e32 v1, v154, v1
	s_movk_i32 s1, 0x90
	s_add_i32 s0, s0, 0
	v_lshlrev_b32_e32 v2, 3, v5
	v_mul_lo_u32 v1, v1, s1
	v_and_b32_e32 v5, 24, v6
	v_add3_u32 v169, s0, v1, v5
	v_add_u32_e32 v1, 64, v246
	v_cmp_lt_i32_e32 vcc, v241, v1
	v_ashrrev_i32_e32 v155, 31, v154
	s_waitcnt vmcnt(9)
	v_not_b32_e32 v10, 63
	v_cndmask_b32_e32 v5, v174, v241, vcc
	v_cmp_lt_i32_e32 vcc, v240, v1
	v_and_b32_e32 v166, 15, v0
	v_lshl_add_u64 v[156:157], v[154:155], 1, s[2:3]
	v_cndmask_b32_e32 v1, v174, v240, vcc
	v_lshlrev_b32_e32 v171, 2, v1
	v_add_u32_e32 v1, 64, v0
	v_ashrrev_i32_e32 v172, 3, v1
	v_add_u32_e32 v1, 0x80, v0
	v_ashrrev_i32_e32 v155, 3, v0
	v_ashrrev_i32_e32 v173, 3, v1
	v_add_u32_e32 v1, 0xc0, v0
	v_lshl_or_b32 v211, v0, 2, v10
	v_add_u32_e32 v0, 0xfff00000, v154
	v_cmp_eq_u32_e64 s[36:37], 0, v0
	v_cmp_eq_u32_e64 s[4:5], -16, v0
	v_add_u32_e32 v0, 0xfff00020, v154
	v_cmp_eq_u32_e64 s[6:7], 0, v0
	v_cmp_eq_u32_e64 s[8:9], -16, v0
	v_add_u32_e32 v0, 0xfff00040, v154
	v_and_b32_e32 v4, 56, v6
	v_ashrrev_i32_e32 v182, 3, v1
	v_cmp_eq_u32_e64 s[10:11], 0, v0
	v_cmp_eq_u32_e64 s[12:13], -16, v0
	v_add_u32_e32 v0, 0xfff00060, v154
	v_lshlrev_b32_e32 v167, 4, v166
	v_ashrrev_i32_e32 v3, 31, v2
	v_lshl_add_u32 v7, v4, 1, s0
	v_or_b32_e32 v8, 0xffffffc0, v166
	v_lshlrev_b32_e32 v170, 2, v5
	v_mul_lo_u32 v1, v155, s1
	v_mul_lo_u32 v5, v172, s1
	v_mul_lo_u32 v6, v173, s1
	v_mul_lo_u32 v9, v182, s1
	v_add_u32_e32 v11, 32, v155
	s_waitcnt vmcnt(8)
	v_add_u32_e32 v12, 32, v172
	v_add_u32_e32 v13, 32, v173
	v_add_u32_e32 v14, 32, v182
	v_add_u32_e32 v15, 64, v155
	s_waitcnt vmcnt(7)
	v_add_u32_e32 v16, 64, v172
	v_add_u32_e32 v17, 64, v173
	v_add_u32_e32 v18, 64, v182
	v_lshlrev_b32_e32 v213, 4, v155
	v_lshlrev_b32_e32 v215, 4, v172
	v_lshlrev_b32_e32 v217, 4, v173
	v_lshlrev_b32_e32 v219, 4, v182
	v_cmp_eq_u32_e64 s[14:15], 0, v0
	v_cmp_eq_u32_e64 s[16:17], -16, v0
	v_add_u32_e32 v0, 0xfff00080, v154
	s_mov_b32 s57, 0
	v_mov_b32_e32 v153, 0
	v_add_u32_e32 v187, 32, v154
	v_add_u32_e32 v192, 64, v154
	v_add_u32_e32 v197, 0x60, v154
	v_add_u32_e32 v198, 0x80, v154
	v_add_u32_e32 v199, 0xa0, v154
	v_add_u32_e32 v195, 0x120, v154
	v_lshlrev_b32_e32 v204, 2, v155
	v_lshlrev_b32_e32 v205, 2, v172
	v_lshlrev_b32_e32 v206, 2, v173
	v_lshlrev_b32_e32 v207, 2, v182
	v_lshlrev_b32_e32 v208, 2, v8
	v_lshlrev_b32_e32 v209, 2, v166
	v_add_u32_e32 v210, 0x140, v154
	v_add_u32_e32 v212, 0x160, v154
	s_mov_b32 s79, s76
	s_bfe_u32 s72, s76, 0x30006
	v_add_u32_e32 v214, 0xfffffc00, v213
	v_add_u32_e32 v216, 0xfffffc00, v215
	v_add_u32_e32 v218, 0xfffffc00, v217
	v_add_u32_e32 v220, 0xfffffc00, v219
	v_lshlrev_b32_e32 v221, 4, v8
	v_add_u32_e32 v222, 0xfffffe00, v213
	v_add_u32_e32 v223, 0xfffffe00, v215
	v_add_u32_e32 v224, 0xfffffe00, v217
	v_add_u32_e32 v225, 0xfffffe00, v219
	v_or_b32_e32 v226, 0xfffffe00, v167
	v_or_b32_e32 v227, 0xffffff00, v167
	v_or_b32_e32 v228, 0x100, v167
	v_lshlrev_b32_e32 v229, 4, v11
	v_lshlrev_b32_e32 v230, 4, v12
	v_lshlrev_b32_e32 v231, 4, v13
	v_lshlrev_b32_e32 v232, 4, v14
	v_or_b32_e32 v233, 0x200, v167
	v_or_b32_e32 v234, 0x300, v167
	v_lshlrev_b32_e32 v235, 4, v15
	v_lshlrev_b32_e32 v236, 4, v16
	v_lshlrev_b32_e32 v237, 4, v17
	v_lshlrev_b32_e32 v238, 4, v18
	v_or_b32_e32 v239, 0x400, v167
	v_or_b32_e32 v240, 0x500, v167
	v_cmp_eq_u32_e64 s[18:19], 0, v0
	v_cmp_eq_u32_e64 s[20:21], -16, v0
	v_lshlrev_b64 v[158:159], 1, v[2:3]
	s_mov_b32 s58, 0x3e38aa3b
	v_lshlrev_b32_e32 v152, 1, v4
	v_add_u32_e32 v241, v7, v1
	v_add_u32_e32 v242, v7, v5
	v_add_u32_e32 v243, v7, v6
	v_add_u32_e32 v244, v7, v9
	s_mov_b32 s73, 0xf149f2ca
	v_mov_b32_e32 v245, 0x178
	v_mov_b32_e32 v246, 0xff800000
	v_mov_b32_e32 v247, 0xbe
	v_mov_b32_e32 v248, 0x8f
	.p2align 6

.Lpk1_LBB0_723:
.Lpk1_LBB0_724:
	s_add_u32 s22, s20, 0x100
	s_addc_u32 s23, s21, 0
	s_and_b64 s[52:53], s[24:25], exec
	s_cselect_b32 s0, 0, s22
	s_add_u32 s52, s49, s20
	s_addc_u32 s53, s50, s21
	s_and_b64 s[20:21], s[24:25], exec
	s_cselect_b32 s21, s15, s53
	s_cselect_b32 s20, s46, s52
	s_add_u32 s98, s2, s0
	s_addc_u32 s99, s3, s1
	s_mov_b32 m0, s28
	s_add_u32 s24, s20, 0x40000
	ds_read_b128 v[180:183], v179 offset:16384
	ds_read_b128 v[184:187], v179 offset:17408
	ds_read_b128 v[188:191], v179 offset:18432
	ds_read_b128 v[192:195], v179 offset:19456
	ds_read_b128 v[196:199], v179 offset:20480
	ds_read_b128 v[200:203], v179 offset:21504
	ds_read_b128 v[204:207], v179 offset:22528
	ds_read_b128 v[208:211], v179 offset:23552
	global_load_lds_dwordx4 v162, s[20:21]
	s_mov_b32 m0, s29
	s_addc_u32 s25, s21, 0
	global_load_lds_dwordx4 v160, s[20:21]
	s_mov_b32 m0, s30
	s_nop 0
	global_load_lds_dwordx4 v162, s[24:25]
	s_mov_b32 m0, s31
	s_nop 0
	global_load_lds_dwordx4 v160, s[24:25]
	s_waitcnt vmcnt(6)
	s_waitcnt lgkmcnt(0)
	s_barrier
	s_setprio 1
	s_waitcnt lgkmcnt(0)
	v_mfma_f32_16x16x32_bf16 v[60:63], v[144:147], v[180:183], 0
	v_mfma_f32_16x16x32_bf16 v[56:59], v[152:155], v[180:183], 0
	v_mfma_f32_16x16x32_bf16 v[48:51], v[144:147], v[188:191], 0
	v_mfma_f32_16x16x32_bf16 v[40:43], v[152:155], v[188:191], 0
	v_mfma_f32_16x16x32_bf16 v[32:35], v[144:147], v[196:199], 0
	v_mfma_f32_16x16x32_bf16 v[24:27], v[152:155], v[196:199], 0
	v_mfma_f32_16x16x32_bf16 v[16:19], v[144:147], v[204:207], 0
	v_mfma_f32_16x16x32_bf16 v[8:11], v[152:155], v[204:207], 0
	v_mfma_f32_16x16x32_bf16 v[60:63], v[148:151], v[184:187], v[60:63]
	v_mfma_f32_16x16x32_bf16 v[56:59], v[156:159], v[184:187], v[56:59]
	v_mfma_f32_16x16x32_bf16 v[48:51], v[148:151], v[192:195], v[48:51]
	v_mfma_f32_16x16x32_bf16 v[40:43], v[156:159], v[192:195], v[40:43]
	v_mfma_f32_16x16x32_bf16 v[32:35], v[148:151], v[200:203], v[32:35]
	v_mfma_f32_16x16x32_bf16 v[24:27], v[156:159], v[200:203], v[24:27]
	v_mfma_f32_16x16x32_bf16 v[16:19], v[148:151], v[208:211], v[16:19]
	v_mfma_f32_16x16x32_bf16 v[8:11], v[156:159], v[208:211], v[8:11]
	v_mfma_f32_16x16x32_bf16 v[52:55], v[128:131], v[180:183], 0
	v_mfma_f32_16x16x32_bf16 v[44:47], v[136:139], v[180:183], 0
	v_mfma_f32_16x16x32_bf16 v[36:39], v[128:131], v[188:191], 0
	v_mfma_f32_16x16x32_bf16 v[28:31], v[136:139], v[188:191], 0
	v_mfma_f32_16x16x32_bf16 v[20:23], v[128:131], v[196:199], 0
	v_mfma_f32_16x16x32_bf16 v[12:15], v[136:139], v[196:199], 0
	v_mfma_f32_16x16x32_bf16 v[4:7], v[128:131], v[204:207], 0
	v_mfma_f32_16x16x32_bf16 v[0:3], v[136:139], v[204:207], 0
	v_mfma_f32_16x16x32_bf16 v[52:55], v[132:135], v[184:187], v[52:55]
	v_mfma_f32_16x16x32_bf16 v[44:47], v[140:143], v[184:187], v[44:47]
	v_mfma_f32_16x16x32_bf16 v[36:39], v[132:135], v[192:195], v[36:39]
	v_mfma_f32_16x16x32_bf16 v[28:31], v[140:143], v[192:195], v[28:31]
	v_mfma_f32_16x16x32_bf16 v[20:23], v[132:135], v[200:203], v[20:23]
	v_mfma_f32_16x16x32_bf16 v[12:15], v[140:143], v[200:203], v[12:15]
	v_mfma_f32_16x16x32_bf16 v[4:7], v[132:135], v[208:211], v[4:7]
	v_mfma_f32_16x16x32_bf16 v[0:3], v[140:143], v[208:211], v[0:3]
	s_setprio 0
	s_barrier
	s_add_i32 s24, 0, 0x18000
	s_add_i32 s25, 0, 0x1c000
	v_add_u32_e32 v140, s24, v176
	v_add_u32_e32 v156, s25, v176
	ds_read_b128 v[128:131], v140
	ds_read_b128 v[132:135], v140 offset:1024
	ds_read_b128 v[136:139], v140 offset:2048
	ds_read_b128 v[140:143], v140 offset:3072
	ds_read_b128 v[144:147], v156
	ds_read_b128 v[148:151], v156 offset:1024
	ds_read_b128 v[152:155], v156 offset:2048
	ds_read_b128 v[156:159], v156 offset:3072
	s_mov_b32 m0, s35
	ds_read_b128 v[180:183], v179 offset:32768
	ds_read_b128 v[184:187], v179 offset:33792
	ds_read_b128 v[188:191], v179 offset:34816
	ds_read_b128 v[192:195], v179 offset:35840
	ds_read_b128 v[196:199], v179 offset:36864
	ds_read_b128 v[200:203], v179 offset:37888
	ds_read_b128 v[204:207], v179 offset:38912
	ds_read_b128 v[208:211], v179 offset:39936
	global_load_lds_dwordx4 v168, s[98:99]
	s_mov_b32 m0, s36
	s_nop 0
	global_load_lds_dwordx4 v170, s[98:99]
	s_mov_b32 m0, s27
	s_nop 0
	global_load_lds_dwordx4 v164, s[98:99]
	s_mov_b32 m0, s34
	s_nop 0
	global_load_lds_dwordx4 v166, s[98:99]
	s_waitcnt vmcnt(8)
	s_waitcnt lgkmcnt(0)
	s_barrier
	s_setprio 1
	s_waitcnt lgkmcnt(0)
	v_mfma_f32_16x16x32_bf16 v[124:127], v[128:131], v[180:183], v[124:127]
	v_mfma_f32_16x16x32_bf16 v[120:123], v[136:139], v[180:183], v[120:123]
	v_mfma_f32_16x16x32_bf16 v[112:115], v[128:131], v[188:191], v[112:115]
	v_mfma_f32_16x16x32_bf16 v[104:107], v[136:139], v[188:191], v[104:107]
	v_mfma_f32_16x16x32_bf16 v[96:99], v[128:131], v[196:199], v[96:99]
	v_mfma_f32_16x16x32_bf16 v[88:91], v[136:139], v[196:199], v[88:91]
	v_mfma_f32_16x16x32_bf16 v[80:83], v[128:131], v[204:207], v[80:83]
	v_mfma_f32_16x16x32_bf16 v[72:75], v[136:139], v[204:207], v[72:75]
	v_mfma_f32_16x16x32_bf16 v[124:127], v[132:135], v[184:187], v[124:127]
	v_mfma_f32_16x16x32_bf16 v[120:123], v[140:143], v[184:187], v[120:123]
	v_mfma_f32_16x16x32_bf16 v[112:115], v[132:135], v[192:195], v[112:115]
	v_mfma_f32_16x16x32_bf16 v[104:107], v[140:143], v[192:195], v[104:107]
	v_mfma_f32_16x16x32_bf16 v[96:99], v[132:135], v[200:203], v[96:99]
	v_mfma_f32_16x16x32_bf16 v[88:91], v[140:143], v[200:203], v[88:91]
	v_mfma_f32_16x16x32_bf16 v[80:83], v[132:135], v[208:211], v[80:83]
	v_mfma_f32_16x16x32_bf16 v[72:75], v[140:143], v[208:211], v[72:75]
	v_mfma_f32_16x16x32_bf16 v[116:119], v[144:147], v[180:183], v[116:119]
	v_mfma_f32_16x16x32_bf16 v[108:111], v[152:155], v[180:183], v[108:111]
	v_mfma_f32_16x16x32_bf16 v[100:103], v[144:147], v[188:191], v[100:103]
	v_mfma_f32_16x16x32_bf16 v[92:95], v[152:155], v[188:191], v[92:95]
	v_mfma_f32_16x16x32_bf16 v[84:87], v[144:147], v[196:199], v[84:87]
	v_mfma_f32_16x16x32_bf16 v[76:79], v[152:155], v[196:199], v[76:79]
	v_mfma_f32_16x16x32_bf16 v[68:71], v[144:147], v[204:207], v[68:71]
	v_mfma_f32_16x16x32_bf16 v[64:67], v[152:155], v[204:207], v[64:67]
	v_mfma_f32_16x16x32_bf16 v[116:119], v[148:151], v[184:187], v[116:119]
	v_mfma_f32_16x16x32_bf16 v[108:111], v[156:159], v[184:187], v[108:111]
	v_mfma_f32_16x16x32_bf16 v[100:103], v[148:151], v[192:195], v[100:103]
	v_mfma_f32_16x16x32_bf16 v[92:95], v[156:159], v[192:195], v[92:95]
	v_mfma_f32_16x16x32_bf16 v[84:87], v[148:151], v[200:203], v[84:87]
	v_mfma_f32_16x16x32_bf16 v[76:79], v[156:159], v[200:203], v[76:79]
	v_mfma_f32_16x16x32_bf16 v[68:71], v[148:151], v[208:211], v[68:71]
	v_mfma_f32_16x16x32_bf16 v[64:67], v[156:159], v[208:211], v[64:67]
	s_setprio 0
	s_barrier
	s_add_i32 s0, s24, s84
	s_add_u32 s100, s20, s6
	s_addc_u32 s101, s21, s7
	s_add_u32 s98, s98, s6
	s_addc_u32 s99, s99, s7
	s_mov_b32 m0, s0
	ds_read_b128 v[180:183], v179 offset:49152
	ds_read_b128 v[184:187], v179 offset:50176
	ds_read_b128 v[188:191], v179 offset:51200
	ds_read_b128 v[192:195], v179 offset:52224
	ds_read_b128 v[196:199], v179 offset:53248
	ds_read_b128 v[200:203], v179 offset:54272
	ds_read_b128 v[204:207], v179 offset:55296
	ds_read_b128 v[208:211], v179 offset:56320
	global_load_lds_dwordx4 v162, s[100:101]
	s_add_i32 m0, s0, 0x2000
	s_add_u32 s20, s20, 0x40080
	s_addc_u32 s21, s21, 0
	s_add_i32 s0, s25, s84
	global_load_lds_dwordx4 v160, s[100:101]
	s_mov_b32 m0, s0
	s_nop 0
	global_load_lds_dwordx4 v162, s[20:21]
	s_add_i32 m0, s0, 0x2000
	s_nop 0
	global_load_lds_dwordx4 v160, s[20:21]
	s_mov_b32 m0, s37
	s_nop 0
	global_load_lds_dwordx4 v164, s[98:99]
	s_mov_b32 m0, s38
	s_nop 0
	global_load_lds_dwordx4 v166, s[98:99]
	s_waitcnt vmcnt(6)
	s_waitcnt lgkmcnt(0)
	s_barrier
	s_setprio 1
	s_waitcnt lgkmcnt(0)
	v_mfma_f32_16x16x32_bf16 v[60:63], v[128:131], v[180:183], v[60:63]
	v_mfma_f32_16x16x32_bf16 v[56:59], v[136:139], v[180:183], v[56:59]
	v_mfma_f32_16x16x32_bf16 v[48:51], v[128:131], v[188:191], v[48:51]
	v_mfma_f32_16x16x32_bf16 v[40:43], v[136:139], v[188:191], v[40:43]
	v_mfma_f32_16x16x32_bf16 v[32:35], v[128:131], v[196:199], v[32:35]
	v_mfma_f32_16x16x32_bf16 v[24:27], v[136:139], v[196:199], v[24:27]
	v_mfma_f32_16x16x32_bf16 v[16:19], v[128:131], v[204:207], v[16:19]
	v_mfma_f32_16x16x32_bf16 v[8:11], v[136:139], v[204:207], v[8:11]
	v_mfma_f32_16x16x32_bf16 v[60:63], v[132:135], v[184:187], v[60:63]
	v_mfma_f32_16x16x32_bf16 v[56:59], v[140:143], v[184:187], v[56:59]
	v_mfma_f32_16x16x32_bf16 v[48:51], v[132:135], v[192:195], v[48:51]
	v_mfma_f32_16x16x32_bf16 v[40:43], v[140:143], v[192:195], v[40:43]
	v_mfma_f32_16x16x32_bf16 v[32:35], v[132:135], v[200:203], v[32:35]
	v_mfma_f32_16x16x32_bf16 v[24:27], v[140:143], v[200:203], v[24:27]
	v_mfma_f32_16x16x32_bf16 v[16:19], v[132:135], v[208:211], v[16:19]
	v_mfma_f32_16x16x32_bf16 v[8:11], v[140:143], v[208:211], v[8:11]
	v_mfma_f32_16x16x32_bf16 v[52:55], v[144:147], v[180:183], v[52:55]
	v_mfma_f32_16x16x32_bf16 v[44:47], v[152:155], v[180:183], v[44:47]
	v_mfma_f32_16x16x32_bf16 v[36:39], v[144:147], v[188:191], v[36:39]
	v_mfma_f32_16x16x32_bf16 v[28:31], v[152:155], v[188:191], v[28:31]
	v_mfma_f32_16x16x32_bf16 v[20:23], v[144:147], v[196:199], v[20:23]
	v_mfma_f32_16x16x32_bf16 v[12:15], v[152:155], v[196:199], v[12:15]
	v_mfma_f32_16x16x32_bf16 v[4:7], v[144:147], v[204:207], v[4:7]
	v_mfma_f32_16x16x32_bf16 v[0:3], v[152:155], v[204:207], v[0:3]
	v_mfma_f32_16x16x32_bf16 v[52:55], v[148:151], v[184:187], v[52:55]
	v_mfma_f32_16x16x32_bf16 v[44:47], v[156:159], v[184:187], v[44:47]
	v_mfma_f32_16x16x32_bf16 v[36:39], v[148:151], v[192:195], v[36:39]
	v_mfma_f32_16x16x32_bf16 v[28:31], v[156:159], v[192:195], v[28:31]
	v_mfma_f32_16x16x32_bf16 v[20:23], v[148:151], v[200:203], v[20:23]
	v_mfma_f32_16x16x32_bf16 v[12:15], v[156:159], v[200:203], v[12:15]
	v_mfma_f32_16x16x32_bf16 v[4:7], v[148:151], v[208:211], v[4:7]
	v_mfma_f32_16x16x32_bf16 v[0:3], v[156:159], v[208:211], v[0:3]
	s_setprio 0
	s_barrier
	s_add_i32 s51, s51, 2
	s_cmp_gt_u32 s51, 13
	s_cbranch_scc1 .LBB0_726
	s_mov_b64 s[20:21], s[22:23]
	s_branch .LBB0_721
	.p2align 6

.Lpk2_LBB0_1250:
.Lpk2_LBB0_1251:
	s_add_u32 s24, s22, 0x100
	s_addc_u32 s25, s23, 0
	s_and_b64 s[70:71], s[26:27], exec
	s_cselect_b32 s6, 0, s24
	s_add_u32 s70, s53, s22
	s_addc_u32 s71, s56, s23
	s_and_b64 s[22:23], s[26:27], exec
	s_cselect_b32 s23, s17, s71
	s_cselect_b32 s22, s50, s70
	s_add_u32 s98, s4, s6
	s_addc_u32 s99, s5, s7
	s_mov_b32 m0, s29
	s_add_u32 s26, s22, 0x20000
	ds_read_b128 v[180:183], v179 offset:16384
	ds_read_b128 v[184:187], v179 offset:17408
	ds_read_b128 v[188:191], v179 offset:18432
	ds_read_b128 v[192:195], v179 offset:19456
	ds_read_b128 v[196:199], v179 offset:20480
	ds_read_b128 v[200:203], v179 offset:21504
	ds_read_b128 v[204:207], v179 offset:22528
	ds_read_b128 v[208:211], v179 offset:23552
	global_load_lds_dwordx4 v162, s[22:23]
	s_mov_b32 m0, s30
	s_addc_u32 s27, s23, 0
	global_load_lds_dwordx4 v160, s[22:23]
	s_mov_b32 m0, s31
	s_nop 0
	global_load_lds_dwordx4 v162, s[26:27]
	s_mov_b32 m0, s34
	s_nop 0
	global_load_lds_dwordx4 v160, s[26:27]
	s_waitcnt vmcnt(6)
	s_waitcnt lgkmcnt(0)
	s_barrier
	s_setprio 1
	s_waitcnt lgkmcnt(0)
	v_mfma_f32_16x16x128_f8f6f4 v[92:95], v[16:23], v[180:187], 0
	v_mfma_f32_16x16x128_f8f6f4 v[88:91], v[24:31], v[180:187], 0
	v_mfma_f32_16x16x128_f8f6f4 v[76:79], v[16:23], v[188:195], 0
	v_mfma_f32_16x16x128_f8f6f4 v[72:75], v[24:31], v[188:195], 0
	v_mfma_f32_16x16x128_f8f6f4 v[212:215], v[16:23], v[196:203], 0
	v_mfma_f32_16x16x128_f8f6f4 v[216:219], v[24:31], v[196:203], 0
	v_mfma_f32_16x16x128_f8f6f4 v[220:223], v[16:23], v[204:211], 0
	v_mfma_f32_16x16x128_f8f6f4 v[224:227], v[24:31], v[204:211], 0
	v_mfma_f32_16x16x128_f8f6f4 v[84:87], v[0:7], v[180:187], 0
	v_mfma_f32_16x16x128_f8f6f4 v[80:83], v[8:15], v[180:187], 0
	v_mfma_f32_16x16x128_f8f6f4 v[68:71], v[0:7], v[188:195], 0
	v_mfma_f32_16x16x128_f8f6f4 v[64:67], v[8:15], v[188:195], 0
	v_mfma_f32_16x16x128_f8f6f4 v[228:231], v[0:7], v[196:203], 0
	v_mfma_f32_16x16x128_f8f6f4 v[196:199], v[8:15], v[196:203], 0
	v_mfma_f32_16x16x128_f8f6f4 v[200:203], v[0:7], v[204:211], 0
	v_mfma_f32_16x16x128_f8f6f4 v[204:207], v[8:15], v[204:211], 0
	s_setprio 0
	s_barrier
	s_add_i32 s26, 0, 0x18000
	s_add_i32 s27, 0, 0x1c000
	v_add_u32_e32 v12, s26, v176
	v_add_u32_e32 v28, s27, v176
	ds_read_b128 v[0:3], v12
	ds_read_b128 v[4:7], v12 offset:1024
	ds_read_b128 v[8:11], v12 offset:2048
	ds_read_b128 v[12:15], v12 offset:3072
	ds_read_b128 v[16:19], v28
	ds_read_b128 v[20:23], v28 offset:1024
	ds_read_b128 v[24:27], v28 offset:2048
	ds_read_b128 v[28:31], v28 offset:3072
	s_mov_b32 m0, s36
	ds_read_b128 v[32:35], v179 offset:32768
	ds_read_b128 v[36:39], v179 offset:33792
	ds_read_b128 v[40:43], v179 offset:34816
	ds_read_b128 v[44:47], v179 offset:35840
	ds_read_b128 v[48:51], v179 offset:36864
	ds_read_b128 v[52:55], v179 offset:37888
	ds_read_b128 v[56:59], v179 offset:38912
	ds_read_b128 v[60:63], v179 offset:39936
	global_load_lds_dwordx4 v168, s[98:99]
	s_mov_b32 m0, s37
	s_nop 0
	global_load_lds_dwordx4 v166, s[98:99]
	s_mov_b32 m0, s28
	s_nop 0
	global_load_lds_dwordx4 v164, s[98:99]
	s_mov_b32 m0, s35
	s_nop 0
	global_load_lds_dwordx4 v170, s[98:99]
	s_waitcnt vmcnt(8)
	s_waitcnt lgkmcnt(0)
	s_barrier
	s_setprio 1
	s_waitcnt lgkmcnt(0)
	v_mfma_f32_16x16x128_f8f6f4 v[156:159], v[0:7], v[32:39], v[156:159]
	v_mfma_f32_16x16x128_f8f6f4 v[152:155], v[8:15], v[32:39], v[152:155]
	v_mfma_f32_16x16x128_f8f6f4 v[140:143], v[0:7], v[40:47], v[140:143]
	v_mfma_f32_16x16x128_f8f6f4 v[136:139], v[8:15], v[40:47], v[136:139]
	v_mfma_f32_16x16x128_f8f6f4 v[124:127], v[0:7], v[48:55], v[124:127]
	v_mfma_f32_16x16x128_f8f6f4 v[120:123], v[8:15], v[48:55], v[120:123]
	v_mfma_f32_16x16x128_f8f6f4 v[108:111], v[0:7], v[56:63], v[108:111]
	v_mfma_f32_16x16x128_f8f6f4 v[104:107], v[8:15], v[56:63], v[104:107]
	v_mfma_f32_16x16x128_f8f6f4 v[148:151], v[16:23], v[32:39], v[148:151]
	v_mfma_f32_16x16x128_f8f6f4 v[144:147], v[24:31], v[32:39], v[144:147]
	v_mfma_f32_16x16x128_f8f6f4 v[132:135], v[16:23], v[40:47], v[132:135]
	v_mfma_f32_16x16x128_f8f6f4 v[128:131], v[24:31], v[40:47], v[128:131]
	v_mfma_f32_16x16x128_f8f6f4 v[116:119], v[16:23], v[48:55], v[116:119]
	v_mfma_f32_16x16x128_f8f6f4 v[112:115], v[24:31], v[48:55], v[112:115]
	v_mfma_f32_16x16x128_f8f6f4 v[100:103], v[16:23], v[56:63], v[100:103]
	v_mfma_f32_16x16x128_f8f6f4 v[96:99], v[24:31], v[56:63], v[96:99]
	s_setprio 0
	s_barrier
	s_add_i32 s6, s26, s84
	s_add_u32 s100, s22, s10
	s_addc_u32 s101, s23, s11
	s_add_u32 s98, s98, s10
	s_addc_u32 s99, s99, s11
	s_mov_b32 m0, s6
	ds_read_b128 v[32:35], v179 offset:49152
	ds_read_b128 v[36:39], v179 offset:50176
	ds_read_b128 v[48:51], v179 offset:51200
	ds_read_b128 v[52:55], v179 offset:52224
	ds_read_b128 v[180:183], v179 offset:53248
	ds_read_b128 v[184:187], v179 offset:54272
	ds_read_b128 v[188:191], v179 offset:55296
	ds_read_b128 v[192:195], v179 offset:56320
	global_load_lds_dwordx4 v162, s[100:101]
	s_add_i32 m0, s6, 0x2000
	s_add_u32 s22, s22, 0x20080
	s_addc_u32 s23, s23, 0
	s_add_i32 s6, s27, s84
	global_load_lds_dwordx4 v160, s[100:101]
	s_mov_b32 m0, s6
	s_nop 0
	global_load_lds_dwordx4 v162, s[22:23]
	s_add_i32 m0, s6, 0x2000
	s_nop 0
	global_load_lds_dwordx4 v160, s[22:23]
	s_mov_b32 m0, s38
	s_nop 0
	global_load_lds_dwordx4 v164, s[98:99]
	s_mov_b32 m0, s39
	s_nop 0
	global_load_lds_dwordx4 v170, s[98:99]
	s_waitcnt vmcnt(6)
	s_waitcnt lgkmcnt(0)
	s_barrier
	s_setprio 1
	s_waitcnt lgkmcnt(0)
	v_mfma_f32_16x16x128_f8f6f4 v[92:95], v[0:7], v[32:39], v[92:95]
	v_mfma_f32_16x16x128_f8f6f4 v[88:91], v[8:15], v[32:39], v[88:91]
	v_mfma_f32_16x16x128_f8f6f4 v[76:79], v[0:7], v[48:55], v[76:79]
	v_mfma_f32_16x16x128_f8f6f4 v[72:75], v[8:15], v[48:55], v[72:75]
	v_mfma_f32_16x16x128_f8f6f4 v[60:63], v[0:7], v[180:187], v[212:215]
	v_mfma_f32_16x16x128_f8f6f4 v[56:59], v[8:15], v[180:187], v[216:219]
	v_mfma_f32_16x16x128_f8f6f4 v[44:47], v[0:7], v[188:195], v[220:223]
	v_mfma_f32_16x16x128_f8f6f4 v[40:43], v[8:15], v[188:195], v[224:227]
	v_mfma_f32_16x16x128_f8f6f4 v[84:87], v[16:23], v[32:39], v[84:87]
	v_mfma_f32_16x16x128_f8f6f4 v[80:83], v[24:31], v[32:39], v[80:83]
	v_mfma_f32_16x16x128_f8f6f4 v[68:71], v[16:23], v[48:55], v[68:71]
	v_mfma_f32_16x16x128_f8f6f4 v[64:67], v[24:31], v[48:55], v[64:67]
	v_mfma_f32_16x16x128_f8f6f4 v[52:55], v[16:23], v[180:187], v[228:231]
	v_mfma_f32_16x16x128_f8f6f4 v[48:51], v[24:31], v[180:187], v[196:199]
	v_mfma_f32_16x16x128_f8f6f4 v[36:39], v[16:23], v[188:195], v[200:203]
	v_mfma_f32_16x16x128_f8f6f4 v[32:35], v[24:31], v[188:195], v[204:207]
	s_setprio 0
	s_barrier
	s_add_i32 s57, s57, 2
	s_cmp_gt_u32 s57, 5
	s_cbranch_scc1 .LBB0_1253
	s_mov_b64 s[22:23], s[24:25]
	s_branch .LBB0_1248
	.p2align 6

.Lpk3_LBB0_1326:
.Lpk3_LBB0_1327:
	s_add_u32 s20, s18, 0x100
	s_addc_u32 s21, s19, 0
	s_and_b64 s[56:57], s[22:23], exec
	s_cselect_b32 s4, 0, s20
	s_add_u32 s53, s50, s18
	s_addc_u32 s56, s51, s19
	s_and_b64 s[18:19], s[22:23], exec
	s_cselect_b32 s19, s15, s56
	s_cselect_b32 s18, s14, s53
	s_add_u32 s98, s2, s4
	s_addc_u32 s99, s3, s5
	s_mov_b32 m0, s26
	s_add_u32 s22, s18, 0x58000
	ds_read_b128 v[178:181], v177 offset:16384
	ds_read_b128 v[182:185], v177 offset:17408
	ds_read_b128 v[186:189], v177 offset:18432
	ds_read_b128 v[190:193], v177 offset:19456
	ds_read_b128 v[194:197], v177 offset:20480
	ds_read_b128 v[198:201], v177 offset:21504
	ds_read_b128 v[202:205], v177 offset:22528
	ds_read_b128 v[206:209], v177 offset:23552
	global_load_lds_dwordx4 v162, s[18:19]
	s_mov_b32 m0, s27
	s_addc_u32 s23, s19, 0
	global_load_lds_dwordx4 v160, s[18:19]
	s_mov_b32 m0, s29
	s_nop 0
	global_load_lds_dwordx4 v162, s[22:23]
	s_mov_b32 m0, s30
	s_nop 0
	global_load_lds_dwordx4 v160, s[22:23]
	s_waitcnt vmcnt(6)
	s_waitcnt lgkmcnt(0)
	s_barrier
	s_setprio 1
	s_waitcnt lgkmcnt(0)
	v_mfma_f32_16x16x128_f8f6f4 v[92:95], v[16:23], v[178:185], 0
	v_mfma_f32_16x16x128_f8f6f4 v[88:91], v[24:31], v[178:185], 0
	v_mfma_f32_16x16x128_f8f6f4 v[76:79], v[16:23], v[186:193], 0
	v_mfma_f32_16x16x128_f8f6f4 v[72:75], v[24:31], v[186:193], 0
	v_mfma_f32_16x16x128_f8f6f4 v[210:213], v[16:23], v[194:201], 0
	v_mfma_f32_16x16x128_f8f6f4 v[214:217], v[24:31], v[194:201], 0
	v_mfma_f32_16x16x128_f8f6f4 v[218:221], v[16:23], v[202:209], 0
	v_mfma_f32_16x16x128_f8f6f4 v[222:225], v[24:31], v[202:209], 0
	v_mfma_f32_16x16x128_f8f6f4 v[84:87], v[0:7], v[178:185], 0
	v_mfma_f32_16x16x128_f8f6f4 v[80:83], v[8:15], v[178:185], 0
	v_mfma_f32_16x16x128_f8f6f4 v[68:71], v[0:7], v[186:193], 0
	v_mfma_f32_16x16x128_f8f6f4 v[64:67], v[8:15], v[186:193], 0
	v_mfma_f32_16x16x128_f8f6f4 v[226:229], v[0:7], v[194:201], 0
	v_mfma_f32_16x16x128_f8f6f4 v[194:197], v[8:15], v[194:201], 0
	v_mfma_f32_16x16x128_f8f6f4 v[198:201], v[0:7], v[202:209], 0
	v_mfma_f32_16x16x128_f8f6f4 v[202:205], v[8:15], v[202:209], 0
	s_setprio 0
	s_barrier
	s_add_i32 s22, 0, 0x18000
	s_add_i32 s23, 0, 0x1c000
	v_add_u32_e32 v12, s22, v173
	v_add_u32_e32 v28, s23, v173
	ds_read_b128 v[0:3], v12
	ds_read_b128 v[4:7], v12 offset:1024
	ds_read_b128 v[8:11], v12 offset:2048
	ds_read_b128 v[12:15], v12 offset:3072
	ds_read_b128 v[16:19], v28
	ds_read_b128 v[20:23], v28 offset:1024
	ds_read_b128 v[24:27], v28 offset:2048
	ds_read_b128 v[28:31], v28 offset:3072
	s_mov_b32 m0, s34
	ds_read_b128 v[32:35], v177 offset:32768
	ds_read_b128 v[36:39], v177 offset:33792
	ds_read_b128 v[40:43], v177 offset:34816
	ds_read_b128 v[44:47], v177 offset:35840
	ds_read_b128 v[48:51], v177 offset:36864
	ds_read_b128 v[52:55], v177 offset:37888
	ds_read_b128 v[56:59], v177 offset:38912
	ds_read_b128 v[60:63], v177 offset:39936
	global_load_lds_dwordx4 v166, s[98:99]
	s_mov_b32 m0, s35
	s_nop 0
	global_load_lds_dwordx4 v170, s[98:99]
	s_mov_b32 m0, s25
	s_nop 0
	global_load_lds_dwordx4 v164, s[98:99]
	s_mov_b32 m0, s31
	s_nop 0
	global_load_lds_dwordx4 v168, s[98:99]
	s_waitcnt vmcnt(8)
	s_waitcnt lgkmcnt(0)
	s_barrier
	s_setprio 1
	s_waitcnt lgkmcnt(0)
	v_mfma_f32_16x16x128_f8f6f4 v[156:159], v[0:7], v[32:39], v[156:159]
	v_mfma_f32_16x16x128_f8f6f4 v[152:155], v[8:15], v[32:39], v[152:155]
	v_mfma_f32_16x16x128_f8f6f4 v[140:143], v[0:7], v[40:47], v[140:143]
	v_mfma_f32_16x16x128_f8f6f4 v[136:139], v[8:15], v[40:47], v[136:139]
	v_mfma_f32_16x16x128_f8f6f4 v[124:127], v[0:7], v[48:55], v[124:127]
	v_mfma_f32_16x16x128_f8f6f4 v[120:123], v[8:15], v[48:55], v[120:123]
	v_mfma_f32_16x16x128_f8f6f4 v[108:111], v[0:7], v[56:63], v[108:111]
	v_mfma_f32_16x16x128_f8f6f4 v[104:107], v[8:15], v[56:63], v[104:107]
	v_mfma_f32_16x16x128_f8f6f4 v[148:151], v[16:23], v[32:39], v[148:151]
	v_mfma_f32_16x16x128_f8f6f4 v[144:147], v[24:31], v[32:39], v[144:147]
	v_mfma_f32_16x16x128_f8f6f4 v[132:135], v[16:23], v[40:47], v[132:135]
	v_mfma_f32_16x16x128_f8f6f4 v[128:131], v[24:31], v[40:47], v[128:131]
	v_mfma_f32_16x16x128_f8f6f4 v[116:119], v[16:23], v[48:55], v[116:119]
	v_mfma_f32_16x16x128_f8f6f4 v[112:115], v[24:31], v[48:55], v[112:115]
	v_mfma_f32_16x16x128_f8f6f4 v[100:103], v[16:23], v[56:63], v[100:103]
	v_mfma_f32_16x16x128_f8f6f4 v[96:99], v[24:31], v[56:63], v[96:99]
	s_setprio 0
	s_barrier
	s_add_i32 s4, s22, s84
	s_add_u32 s100, s18, s10
	s_addc_u32 s101, s19, s11
	s_add_u32 s98, s98, s10
	s_addc_u32 s99, s99, s11
	s_mov_b32 m0, s4
	ds_read_b128 v[32:35], v177 offset:49152
	ds_read_b128 v[36:39], v177 offset:50176
	ds_read_b128 v[48:51], v177 offset:51200
	ds_read_b128 v[52:55], v177 offset:52224
	ds_read_b128 v[178:181], v177 offset:53248
	ds_read_b128 v[182:185], v177 offset:54272
	ds_read_b128 v[186:189], v177 offset:55296
	ds_read_b128 v[190:193], v177 offset:56320
	global_load_lds_dwordx4 v162, s[100:101]
	s_add_i32 m0, s4, 0x2000
	s_add_u32 s18, s18, 0x58080
	s_addc_u32 s19, s19, 0
	s_add_i32 s4, s23, s84
	global_load_lds_dwordx4 v160, s[100:101]
	s_mov_b32 m0, s4
	s_nop 0
	global_load_lds_dwordx4 v162, s[18:19]
	s_add_i32 m0, s4, 0x2000
	s_nop 0
	global_load_lds_dwordx4 v160, s[18:19]
	s_mov_b32 m0, s36
	s_nop 0
	global_load_lds_dwordx4 v164, s[98:99]
	s_mov_b32 m0, s37
	s_nop 0
	global_load_lds_dwordx4 v168, s[98:99]
	s_waitcnt vmcnt(6)
	s_waitcnt lgkmcnt(0)
	s_barrier
	s_setprio 1
	s_waitcnt lgkmcnt(0)
	v_mfma_f32_16x16x128_f8f6f4 v[92:95], v[0:7], v[32:39], v[92:95]
	v_mfma_f32_16x16x128_f8f6f4 v[88:91], v[8:15], v[32:39], v[88:91]
	v_mfma_f32_16x16x128_f8f6f4 v[76:79], v[0:7], v[48:55], v[76:79]
	v_mfma_f32_16x16x128_f8f6f4 v[72:75], v[8:15], v[48:55], v[72:75]
	v_mfma_f32_16x16x128_f8f6f4 v[60:63], v[0:7], v[178:185], v[210:213]
	v_mfma_f32_16x16x128_f8f6f4 v[56:59], v[8:15], v[178:185], v[214:217]
	v_mfma_f32_16x16x128_f8f6f4 v[44:47], v[0:7], v[186:193], v[218:221]
	v_mfma_f32_16x16x128_f8f6f4 v[40:43], v[8:15], v[186:193], v[222:225]
	v_mfma_f32_16x16x128_f8f6f4 v[84:87], v[16:23], v[32:39], v[84:87]
	v_mfma_f32_16x16x128_f8f6f4 v[80:83], v[24:31], v[32:39], v[80:83]
	v_mfma_f32_16x16x128_f8f6f4 v[68:71], v[16:23], v[48:55], v[68:71]
	v_mfma_f32_16x16x128_f8f6f4 v[64:67], v[24:31], v[48:55], v[64:67]
	v_mfma_f32_16x16x128_f8f6f4 v[52:55], v[16:23], v[178:185], v[226:229]
	v_mfma_f32_16x16x128_f8f6f4 v[48:51], v[24:31], v[178:185], v[194:197]
	v_mfma_f32_16x16x128_f8f6f4 v[36:39], v[16:23], v[186:193], v[198:201]
	v_mfma_f32_16x16x128_f8f6f4 v[32:35], v[24:31], v[186:193], v[202:205]
	s_setprio 0
	s_barrier
	s_add_i32 s52, s52, 2
	s_cmp_gt_u32 s52, 19
	s_cbranch_scc1 .LBB0_1329
	s_mov_b64 s[18:19], s[20:21]
	s_branch .LBB0_1324
	.p2align 6
